# hand-written grid-barrier leader block (8 of 9 copies): barrier index kept in LDS instead of two integer divisions, plain spin on the arrival counter, no time-out bookkeeping; write-back also dropped
# speedup vs baseline: 1.0178x; 1.0001x over previous
.LBB0_139:
	s_load_dwordx2 s[6:7], s[0:1], 0x100
	s_waitcnt vmcnt(0)
	s_waitcnt lgkmcnt(0)
	s_barrier
	s_and_saveexec_b64 s[4:5], s[8:9]
	s_cbranch_execz .LBB0_191
	s_waitcnt vmcnt(0) lgkmcnt(0)
	s_and_b32 s20, s2, 15
	s_lshl_b32 s20, s20, 8
	s_add_u32 s16, s6, 0xe800000
	s_addc_u32 s17, s7, 0
	s_add_u32 s18, s16, s20
	s_addc_u32 s19, s17, 0
	v_mov_b32_e32 v0, 0x20160
	ds_read2_b32 v[2:3], v0 offset1:1
	ds_read_b32 v4, v0 offset:16
	v_mov_b32_e32 v5, 0
	v_mov_b32_e32 v6, 1
	s_waitcnt lgkmcnt(0)
	v_cmp_ne_u32_e32 vcc, 0, v2
	s_cbranch_vccnz .Lgb1_go
	s_add_u32 s22, s16, 0x400
	s_addc_u32 s23, s17, 0
	s_add_u32 s24, s16, 0xc00
	s_addc_u32 s25, s17, 0
.Lgb1_su:
	v_mov_b32_e32 v14, 0
	v_mov_b32_e32 v15, 0
	global_load_dword v7, v5, s[22:23] sc1
	global_load_dword v8, v5, s[22:23] offset:256 sc1
	global_load_dword v9, v5, s[22:23] offset:512 sc1
	global_load_dword v10, v5, s[22:23] offset:768 sc1
	global_load_dword v11, v5, s[22:23] offset:1024 sc1
	global_load_dword v12, v5, s[22:23] offset:1280 sc1
	global_load_dword v13, v5, s[22:23] offset:1536 sc1
	global_load_dword v16, v5, s[22:23] offset:1792 sc1
	s_waitcnt vmcnt(0)
	v_add_u32_e32 v14, v14, v7
	v_cmp_ne_u32_e32 vcc, 0, v7
	s_nop 1
	v_addc_co_u32_e32 v15, vcc, 0, v15, vcc
	v_add_u32_e32 v14, v14, v8
	v_cmp_ne_u32_e32 vcc, 0, v8
	s_nop 1
	v_addc_co_u32_e32 v15, vcc, 0, v15, vcc
	v_add_u32_e32 v14, v14, v9
	v_cmp_ne_u32_e32 vcc, 0, v9
	s_nop 1
	v_addc_co_u32_e32 v15, vcc, 0, v15, vcc
	v_add_u32_e32 v14, v14, v10
	v_cmp_ne_u32_e32 vcc, 0, v10
	s_nop 1
	v_addc_co_u32_e32 v15, vcc, 0, v15, vcc
	v_add_u32_e32 v14, v14, v11
	v_cmp_ne_u32_e32 vcc, 0, v11
	s_nop 1
	v_addc_co_u32_e32 v15, vcc, 0, v15, vcc
	v_add_u32_e32 v14, v14, v12
	v_cmp_ne_u32_e32 vcc, 0, v12
	s_nop 1
	v_addc_co_u32_e32 v15, vcc, 0, v15, vcc
	v_add_u32_e32 v14, v14, v13
	v_cmp_ne_u32_e32 vcc, 0, v13
	s_nop 1
	v_addc_co_u32_e32 v15, vcc, 0, v15, vcc
	v_add_u32_e32 v14, v14, v16
	v_cmp_ne_u32_e32 vcc, 0, v16
	s_nop 1
	v_addc_co_u32_e32 v15, vcc, 0, v15, vcc
	global_load_dword v7, v5, s[24:25] sc1
	global_load_dword v8, v5, s[24:25] offset:256 sc1
	global_load_dword v9, v5, s[24:25] offset:512 sc1
	global_load_dword v10, v5, s[24:25] offset:768 sc1
	global_load_dword v11, v5, s[24:25] offset:1024 sc1
	global_load_dword v12, v5, s[24:25] offset:1280 sc1
	global_load_dword v13, v5, s[24:25] offset:1536 sc1
	global_load_dword v16, v5, s[24:25] offset:1792 sc1
	s_waitcnt vmcnt(0)
	v_add_u32_e32 v14, v14, v7
	v_cmp_ne_u32_e32 vcc, 0, v7
	s_nop 1
	v_addc_co_u32_e32 v15, vcc, 0, v15, vcc
	v_add_u32_e32 v14, v14, v8
	v_cmp_ne_u32_e32 vcc, 0, v8
	s_nop 1
	v_addc_co_u32_e32 v15, vcc, 0, v15, vcc
	v_add_u32_e32 v14, v14, v9
	v_cmp_ne_u32_e32 vcc, 0, v9
	s_nop 1
	v_addc_co_u32_e32 v15, vcc, 0, v15, vcc
	v_add_u32_e32 v14, v14, v10
	v_cmp_ne_u32_e32 vcc, 0, v10
	s_nop 1
	v_addc_co_u32_e32 v15, vcc, 0, v15, vcc
	v_add_u32_e32 v14, v14, v11
	v_cmp_ne_u32_e32 vcc, 0, v11
	s_nop 1
	v_addc_co_u32_e32 v15, vcc, 0, v15, vcc
	v_add_u32_e32 v14, v14, v12
	v_cmp_ne_u32_e32 vcc, 0, v12
	s_nop 1
	v_addc_co_u32_e32 v15, vcc, 0, v15, vcc
	v_add_u32_e32 v14, v14, v13
	v_cmp_ne_u32_e32 vcc, 0, v13
	s_nop 1
	v_addc_co_u32_e32 v15, vcc, 0, v15, vcc
	v_add_u32_e32 v14, v14, v16
	v_cmp_ne_u32_e32 vcc, 0, v16
	s_nop 1
	v_addc_co_u32_e32 v15, vcc, 0, v15, vcc
	v_cmp_eq_u32_e32 vcc, 0x100, v14
	s_cbranch_vccnz .Lgb1_sd
	s_sleep 1
	s_branch .Lgb1_su
.Lgb1_sd:
	global_load_dword v2, v5, s[18:19] offset:1024 sc1
	v_max_u32_e32 v3, 1, v15
	s_waitcnt vmcnt(0)
	v_max_u32_e32 v2, 1, v2
	ds_write2_b32 v0, v2, v3 offset1:1
.Lgb1_go:
	v_mov_b32_e32 v7, 0x1000
	global_atomic_add v7, v7, v6, s[18:19] offset:1024 sc0
	v_add_u32_e32 v8, 1, v4
	v_mul_lo_u32 v9, v8, v2
	v_mul_lo_u32 v10, v8, v3
	ds_write_b32 v0, v8 offset:16
	v_mov_b32_e32 v11, 0x3000
	s_waitcnt vmcnt(0)
	v_add_u32_e32 v7, 1, v7
	v_cmp_ne_u32_e32 vcc, v7, v9
	s_cbranch_vccnz .Lgb1_poll
	buffer_wbl2 sc1
	s_waitcnt vmcnt(0)
	global_atomic_add v11, v6, s[16:17] offset:1024
.Lgb1_poll:
	global_load_dword v12, v11, s[16:17] offset:1024 sc1
	s_waitcnt vmcnt(0)
	v_cmp_le_u32_e32 vcc, v10, v12
	s_cbranch_vccnz .Lgb1_rel
	s_sleep 1
	s_branch .Lgb1_poll
.Lgb1_rel:
	buffer_inv sc1
	s_waitcnt vmcnt(0) lgkmcnt(0)

.LBB0_336:
	s_waitcnt vmcnt(0)
	s_waitcnt lgkmcnt(0)
	s_barrier
	s_and_saveexec_b64 s[4:5], s[8:9]
	v_readlane_b32 s51, v255, 33
	v_readlane_b32 s50, v255, 11
	s_cbranch_execz .LBB0_388
	s_waitcnt vmcnt(0) lgkmcnt(0)
	s_and_b32 s20, s0, 15
	s_lshl_b32 s20, s20, 8
	s_add_u32 s16, s6, 0xe800000
	s_addc_u32 s17, s7, 0
	s_add_u32 s18, s16, s20
	s_addc_u32 s19, s17, 0
	v_mov_b32_e32 v0, 0x20160
	ds_read2_b32 v[2:3], v0 offset1:1
	ds_read_b32 v4, v0 offset:16
	v_mov_b32_e32 v5, 0
	v_mov_b32_e32 v6, 1
	s_waitcnt lgkmcnt(0)
	v_cmp_ne_u32_e32 vcc, 0, v2
	s_cbranch_vccnz .Lgb2_go
	s_add_u32 s22, s16, 0x400
	s_addc_u32 s23, s17, 0
	s_add_u32 s24, s16, 0xc00
	s_addc_u32 s25, s17, 0

.LBB0_461:
	s_waitcnt vmcnt(0)
	s_waitcnt vmcnt(0) lgkmcnt(0)
	s_barrier
	s_and_saveexec_b64 s[4:5], s[8:9]
	s_cbranch_execz .LBB0_514
	s_waitcnt vmcnt(0) lgkmcnt(0)
	s_and_b32 s20, s0, 15
	s_lshl_b32 s20, s20, 8
	s_add_u32 s16, s6, 0xe800000
	s_addc_u32 s17, s7, 0
	s_add_u32 s18, s16, s20
	s_addc_u32 s19, s17, 0
	v_mov_b32_e32 v0, 0x20160
	ds_read2_b32 v[2:3], v0 offset1:1
	ds_read_b32 v4, v0 offset:16
	v_mov_b32_e32 v5, 0
	v_mov_b32_e32 v6, 1
	s_waitcnt lgkmcnt(0)
	v_cmp_ne_u32_e32 vcc, 0, v2
	s_cbranch_vccnz .Lgb3_go
	s_add_u32 s22, s16, 0x400
	s_addc_u32 s23, s17, 0
	s_add_u32 s24, s16, 0xc00
	s_addc_u32 s25, s17, 0

.Lgb3_go:
	v_mov_b32_e32 v7, 0x1000
	global_atomic_add v7, v7, v6, s[18:19] offset:1024 sc0
	v_add_u32_e32 v8, 1, v4
	v_mul_lo_u32 v9, v8, v2
	v_mul_lo_u32 v10, v8, v3
	ds_write_b32 v0, v8 offset:16
	v_mov_b32_e32 v11, 0x3000
	s_waitcnt vmcnt(0)
	v_add_u32_e32 v7, 1, v7
	v_cmp_ne_u32_e32 vcc, v7, v9
	s_cbranch_vccnz .Lgb3_poll
	global_atomic_add v11, v6, s[16:17] offset:1024

.LBB0_902:
	s_waitcnt vmcnt(0)
	s_waitcnt lgkmcnt(0)
	s_barrier
	s_and_saveexec_b64 s[4:5], s[8:9]
	v_readlane_b32 s86, v255, 1
	s_movk_i32 s50, 0x300
	v_readlane_b32 s52, v254, 55
	s_mov_b64 s[54:55], 0x800
	s_cbranch_execz .LBB0_955
	s_waitcnt vmcnt(0) lgkmcnt(0)
	s_and_b32 s20, s0, 15
	s_lshl_b32 s20, s20, 8
	s_add_u32 s16, s6, 0xe800000
	s_addc_u32 s17, s7, 0
	s_add_u32 s18, s16, s20
	s_addc_u32 s19, s17, 0
	v_mov_b32_e32 v0, 0x20160
	ds_read2_b32 v[2:3], v0 offset1:1
	ds_read_b32 v4, v0 offset:16
	v_mov_b32_e32 v5, 0
	v_mov_b32_e32 v6, 1
	s_waitcnt lgkmcnt(0)
	v_cmp_ne_u32_e32 vcc, 0, v2
	s_cbranch_vccnz .Lgb6_go
	s_add_u32 s22, s16, 0x400
	s_addc_u32 s23, s17, 0
	s_add_u32 s24, s16, 0xc00
	s_addc_u32 s25, s17, 0

.LBB0_1201:
	s_waitcnt vmcnt(0)
	s_waitcnt lgkmcnt(0)
	s_barrier
	s_and_saveexec_b64 s[6:7], s[10:11]
	s_cbranch_execz .LBB0_1253
	s_waitcnt vmcnt(0) lgkmcnt(0)
	s_and_b32 s20, s0, 15
	s_lshl_b32 s20, s20, 8
	s_add_u32 s16, s8, 0xe800000
	s_addc_u32 s17, s9, 0
	s_add_u32 s18, s16, s20
	s_addc_u32 s19, s17, 0
	v_mov_b32_e32 v0, 0x20160
	ds_read2_b32 v[2:3], v0 offset1:1
	ds_read_b32 v4, v0 offset:16
	v_mov_b32_e32 v5, 0
	v_mov_b32_e32 v6, 1
	s_waitcnt lgkmcnt(0)
	v_cmp_ne_u32_e32 vcc, 0, v2
	s_cbranch_vccnz .Lgb7_go
	s_add_u32 s22, s16, 0x400
	s_addc_u32 s23, s17, 0
	s_add_u32 s24, s16, 0xc00
	s_addc_u32 s25, s17, 0

.LBB0_1337:
	v_mov_b32_e32 v2, 0x20170
	v_mov_b32_e32 v3, 1
	ds_add_u32 v2, v3
	v_readlane_b32 s1, v254, 51
	s_waitcnt vmcnt(0) expcnt(0) lgkmcnt(0)
	s_and_b32 s0, s0, 15
	v_mov_b32_e32 v0, s1
	ds_read_b32 v3, v0
	v_readlane_b32 s1, v254, 52
	s_waitcnt lgkmcnt(0)
	v_cmp_ne_u32_e32 vcc, 0, v3
	v_mov_b32_e32 v0, s1
	ds_read_b32 v2, v0
	s_cbranch_vccnz .LBB0_1353
	s_add_u32 s8, s6, 0xe800200
	s_addc_u32 s9, s7, 0
	s_add_u32 s10, s6, 0xe800400
	s_addc_u32 s11, s7, 0
	s_add_u32 s12, s6, 0xe800500
	s_addc_u32 s13, s7, 0
	s_add_u32 s14, s6, 0xe800600
	s_addc_u32 s15, s7, 0
	s_add_u32 s16, s6, 0xe800700
	s_addc_u32 s17, s7, 0
	s_add_u32 s18, s6, 0xe800800
	s_addc_u32 s19, s7, 0
	s_add_u32 s20, s6, 0xe800900
	s_addc_u32 s21, s7, 0
	s_add_u32 s22, s6, 0xe800a00
	s_addc_u32 s23, s7, 0
	s_add_u32 s24, s6, 0xe800b00
	s_addc_u32 s25, s7, 0
	s_add_u32 s26, s6, 0xe800c00
	s_addc_u32 s27, s7, 0
	s_add_u32 s28, s6, 0xe800d00
	s_addc_u32 s29, s7, 0
	s_add_u32 s30, s6, 0xe800e00
	s_addc_u32 s31, s7, 0
	s_add_u32 s34, s6, 0xe800f00
	s_addc_u32 s35, s7, 0
	s_add_u32 s36, s6, 0xe801000
	s_addc_u32 s37, s7, 0
	s_add_u32 s38, s6, 0xe801100
	s_addc_u32 s39, s7, 0
	s_add_u32 s40, s6, 0xe801200
	s_addc_u32 s41, s7, 0
	s_add_u32 s42, s6, 0xe801300
	s_addc_u32 s43, s7, 0
	s_mov_b32 s1, 1
	s_branch .LBB0_1341

.LBB0_1370:
	s_mov_b64 s[10:11], exec
	s_waitcnt lgkmcnt(0)
	s_waitcnt vmcnt(0)
	v_mbcnt_lo_u32_b32 v0, s10, 0
	v_mbcnt_hi_u32_b32 v0, s11, v0
	v_cmp_eq_u32_e32 vcc, 0, v0
	s_and_saveexec_b64 s[12:13], vcc
	s_cbranch_execz .LBB0_1372
	s_bcnt1_i32_b64 s0, s[10:11]
	v_mov_b32_e32 v3, s0
	v_mov_b32_e32 v4, 0xe803000
	global_atomic_add v3, v4, v3, s[6:7] offset:1024 sc0
